# weight-conversion store side: hipcc's flag-pair lowering of the 3-way kind switch (108 scalar/branch instructions) rewritten by hand as compare-and-branch with one path per kind (59 instructions)
# speedup vs baseline: 1.0000x; 1.0000x over previous
; __device__ __forceinline__ CvU cv_decode(ArgsP a, unsigned char* ws, int hi, int layer) {
;     CvU u; int fi = hi >> 1; const int half = hi & 1; int l = layer, kind;
;     if (fi < CV_GLU) kind = 0; else if ((fi -= CV_GLU) < CV_OUT) kind = 1; else { fi -= CV_OUT; kind = 2; l = layer + 1; }
;     int kb, nb;
;     if (kind == 0) { u.W = a->in[I_WGLU] + (size_t)l * DS * DS; u.WT = (bf16_t*)(ws + WS_WTGLU + (size_t)l * DS * DS); u.K = DS; u.N = DS; kb = fi / (DS / 64); nb = fi % (DS / 64); }
;     else if (kind == 1) { u.W = a->in[I_WOUT] + (size_t)l * DM * DM; u.WT = (bf16_t*)(ws + WS_WTOUT) + (size_t)l * DM * DM; u.K = DM; u.N = DM; kb = fi / (DM / 64); nb = fi % (DM / 64); }
;     else { u.W = a->in[I_WIN] + (size_t)l * DM * NPROJ; u.WT = (bf16_t*)(ws + WS_WTIN) + (size_t)l * NPROJ * DM; u.K = DM; u.N = NPROJ; kb = fi / (NPROJ / 64); nb = fi % (NPROJ / 64); }
;     u.k0 = 64 * kb + 32 * half; u.n0 = 64 * nb; u.n0d = u.n0; u.rowperm = 0;
;     u.ks = nullptr; u.f8 = (kind == 0);
;     if (kind == 1) u.ks = (u.k0 < DS) ? a->in[I_SNW] + l * DS + u.k0 : a->in[I_RNW] + l * DR + (u.k0 - DS);
;     if (kind == 2) { u.ks = a->in[I_NORMW] + l * DM + u.k0;
;         int n0 = u.n0; if (n0 >= 10240) n0 -= 2048; else if (n0 >= 8192) n0 += 2048;
;         if (n0 >= 4096 && n0 < 8192) { const int m = (n0 >> 6) & 3; n0 = (n0 & ~255) + 128 * (m & 1) + 32 * (m >> 1); u.rowperm = 1; }
;         u.n0d = n0; }
.Lrk_wd:
	s_and_b64 vcc, exec, s[38:39]
	s_cbranch_vccnz .LBB0_357
	s_ashr_i32 s14, s36, 1
	s_mov_b64 s[6:7], -1
	s_mov_b64 s[46:47], -1
	s_cmpk_lt_i32 s14, 0x400
	s_cbranch_scc1 .Lsd_glu
	s_mov_b64 s[38:39], -1
	s_cmpk_gt_u32 s14, 0x13ff
	s_cbranch_scc1 .Lsd_win
	s_add_i32 s14, s14, 0xfffffc00
	s_lshl_b64 s[4:5], s[48:49], 25
	s_add_u32 s4, s8, s4
	s_addc_u32 s5, s94, s5
	s_lshr_b32 s15, s14, 6
	s_and_b32 s76, s14, 63
	s_mov_b32 s12, 0x1000
	s_lshl_b32 s13, s76, 6
	s_branch .LBB0_406
.Lsd_glu:
	s_mov_b64 s[38:39], 0
	s_lshl_b64 s[4:5], s[48:49], 22
	s_add_u32 s4, s9, s4
	s_addc_u32 s5, s58, s5
	s_lshr_b32 s15, s14, 5
	s_and_b32 s76, s14, 31
	s_movk_i32 s12, 0x800
	s_lshl_b32 s13, s76, 6
	s_branch .LBB0_406
.Lsd_win:
	s_add_i32 s14, s14, 0xffffec00
	s_mul_i32 s4, s54, 0x6000000
	s_mul_hi_i32 s5, s54, 0x6000000
	s_add_u32 s4, s59, s4
	s_addc_u32 s5, s53, s5
	s_mul_hi_i32 s12, s14, 0x2aaaaaab
	s_lshr_b32 s13, s12, 31
	s_ashr_i32 s12, s12, 5
	s_add_i32 s15, s12, s13
	s_mul_i32 s12, s15, 0xc0
	s_sub_i32 s76, s14, s12
	s_mov_b32 s12, 0x1000
	s_lshl_b32 s13, s76, 6
	s_add_i32 s14, s13, 0xfffff800
	s_add_i32 s46, s13, 0x800
	s_cmpk_gt_i32 s76, 0x7f
	s_cselect_b32 s13, s46, s13
	s_cmpk_gt_i32 s76, 0x9f
	s_cselect_b32 s13, s14, s13
	s_lshl_b32 s47, s13, 1
	s_and_b32 s46, s13, 0x1f00
	s_and_b32 s47, s47, 0x80
	s_or_b32 s46, s47, s46
	s_lshr_b32 s47, s13, 2
	s_and_b32 s47, s47, 32
	s_and_b32 s14, s13, 0xfffff000
	s_or_b32 s76, s46, s47
	s_cmpk_lg_i32 s14, 0x1000
	s_cselect_b64 s[46:47], -1, 0
	s_and_b64 s[70:71], s[46:47], exec
	s_cselect_b32 s13, s13, s76
